# differential-attention loop: next tile's running-max chain, rescale decision and first-half exp2 arguments moved into the issue shadows of the P*V MFMAs (MFMA/VALU interleave)
# baseline (speedup 1.0000x reference)
.LBB0_1085:
	ds_read_b128 v[64:67], v181 offset:40960
	ds_read_b128 v[68:71], v181 offset:45056
	v_exp_f32_e32 v194, v136
	v_pk_add_f32 v[190:191], v[144:145], v[146:147]
	v_pk_add_f32 v[190:191], v[190:191], v[148:149]
	s_waitcnt lgkmcnt(1)
	v_mfma_f32_32x32x16_bf16 v[80:95], v[64:67], v[108:111], 0
	v_pk_add_f32 v[190:191], v[190:191], v[150:151]
	v_pk_add_f32 v[190:191], v[190:191], v[160:161]
	ds_read_b128 v[198:201], v187 offset:40960
	ds_read_b128 v[202:205], v187 offset:45056
	v_pk_add_f32 v[190:191], v[190:191], v[162:163]
	v_pk_add_f32 v[190:191], v[190:191], v[142:143]
	s_waitcnt lgkmcnt(2)
	v_mfma_f32_32x32x16_bf16 v[64:79], v[68:71], v[108:111], 0
	v_exp_f32_e32 v141, v138
	v_exp_f32_e32 v192, v139
	s_waitcnt lgkmcnt(1)
	v_mfma_f32_32x32x16_bf16 v[80:95], v[198:201], v[100:103], v[80:95]
	v_exp_f32_e32 v195, v137
	v_exp_f32_e32 v132, v132
	v_exp_f32_e32 v133, v133
	v_pk_add_f32 v[190:191], v[190:191], v[192:193]
	s_waitcnt lgkmcnt(0)
	v_mfma_f32_32x32x16_bf16 v[64:79], v[202:205], v[100:103], v[64:79]
	ds_read_b128 v[198:201], v188 offset:40960
	ds_read_b128 v[202:205], v188 offset:45056
	v_exp_f32_e32 v128, v128
	v_exp_f32_e32 v129, v129
	v_pk_add_f32 v[190:191], v[190:191], v[194:195]
	v_exp_f32_e32 v126, v126
	s_waitcnt lgkmcnt(1)
	v_mfma_f32_32x32x16_bf16 v[80:95], v[198:201], v[96:99], v[80:95]
	v_pk_add_f32 v[190:191], v[190:191], v[132:133]
	v_exp_f32_e32 v127, v127
	v_exp_f32_e32 v134, v134
	v_pk_add_f32 v[190:191], v[190:191], v[128:129]
	v_exp_f32_e32 v135, v135
	s_waitcnt lgkmcnt(0)
	v_mfma_f32_32x32x16_bf16 v[64:79], v[202:205], v[96:99], v[64:79]
	ds_read_b128 v[198:201], v176 offset:40960
	ds_read_b128 v[202:205], v176 offset:45056
	v_exp_f32_e32 v130, v130
	v_pk_add_f32 v[190:191], v[190:191], v[126:127]
	v_exp_f32_e32 v131, v131
	v_exp_f32_e32 v124, v124
	v_pk_add_f32 v[190:191], v[190:191], v[134:135]
	s_waitcnt lgkmcnt(1)
	v_mfma_f32_32x32x16_bf16 v[80:95], v[198:201], v[104:107], v[80:95]
	v_exp_f32_e32 v125, v125
	v_pk_add_f32 v[190:191], v[190:191], v[130:131]
	v_add_f32_e32 v136, v196, v141
	v_pk_add_f32 v[190:191], v[190:191], v[124:125]
	v_add_f32_e32 v190, v190, v191
	v_add_f32_e32 v190, v136, v190
	v_mov_b32_e32 v191, v190
	s_waitcnt lgkmcnt(0)
	v_mfma_f32_32x32x16_bf16 v[64:79], v[202:205], v[104:107], v[64:79]
	v_cvt_pk_bf16_f32 v136, v144, v146
	v_cvt_pk_bf16_f32 v138, v160, v162
	v_cvt_pk_bf16_f32 v142, v142, v143
	v_cvt_pk_bf16_f32 v143, v145, v147
	v_cvt_pk_bf16_f32 v146, v141, v192
	v_cvt_pk_bf16_f32 v147, v194, v195
	v_cvt_pk_bf16_f32 v192, v126, v127
	v_cvt_pk_bf16_f32 v194, v130, v131
	v_permlane32_swap_b32_e32 v190, v191
	v_cvt_pk_bf16_f32 v137, v148, v150
	v_cvt_pk_bf16_f32 v139, v163, v196
	v_permlane32_swap_b32_e32 v136, v138
	v_cvt_pk_bf16_f32 v144, v149, v151
	v_cvt_pk_bf16_f32 v145, v161, v193
	v_cvt_pk_bf16_f32 v148, v132, v133
	v_cvt_pk_bf16_f32 v149, v128, v129
	v_cvt_pk_bf16_f32 v193, v134, v135
	v_cvt_pk_bf16_f32 v195, v124, v125
	v_permlane32_swap_b32_e32 v192, v194
	v_permlane32_swap_b32_e32 v137, v139
	v_permlane32_swap_b32_e32 v142, v144
	v_permlane32_swap_b32_e32 v143, v145
	v_permlane32_swap_b32_e32 v146, v148
	v_permlane32_swap_b32_e32 v147, v149
	v_permlane32_swap_b32_e32 v193, v195
	v_lshl_add_u64 v[160:161], v[158:159], 0, s[30:31]
	v_add_co_u32_e32 v124, vcc, s39, v160
	s_mov_b32 s4, 0x186c0000
	s_nop 0
	v_addc_co_u32_e32 v125, vcc, 0, v161, vcc
	v_add_co_u32_e32 v128, vcc, s4, v160
	v_lshl_add_u64 v[162:163], v[156:157], 0, s[30:31]
	s_nop 0
	v_addc_co_u32_e32 v129, vcc, 0, v161, vcc
	v_add_co_u32_e32 v132, vcc, s39, v162
	global_load_dwordx4 v[124:127], v[124:125], off offset:3072
	s_nop 0
	global_load_dwordx4 v[128:131], v[128:129], off offset:3072
	v_addc_co_u32_e32 v133, vcc, 0, v163, vcc
	global_load_dwordx4 v[132:135], v[132:133], off offset:1536
	ds_read_b64_tr_b16 v[196:197], v175 offset:0
	ds_read_b64_tr_b16 v[198:199], v175 offset:0x800
	ds_read_b64_tr_b16 v[200:201], v175 offset:0x1000
	ds_read_b64_tr_b16 v[202:203], v175 offset:0x1800
	ds_read_b64_tr_b16 v[204:205], v175 offset:0x2000
	ds_read_b64_tr_b16 v[206:207], v175 offset:0x2800
	ds_read_b64_tr_b16 v[208:209], v175 offset:0x3000
	ds_read_b64_tr_b16 v[210:211], v175 offset:0x3800
	s_waitcnt lgkmcnt(0)
	s_nop 0
	v_mfma_f32_32x32x16_bf16 v[0:15], v[136:139], v[196:199], v[0:15]
	v_max_f32_e32 v248, v81, v81
	v_max_f32_e32 v249, v80, v80
	v_max_f32_e32 v248, v249, v248
	v_max3_f32 v248, v248, v82, v83
	ds_read_b64_tr_b16 v[196:197], v175 offset:0x200
	ds_read_b64_tr_b16 v[198:199], v175 offset:0xa00
	v_mfma_f32_32x32x16_bf16 v[0:15], v[142:145], v[200:203], v[0:15]
	v_max3_f32 v248, v248, v84, v85
	v_max3_f32 v248, v248, v86, v87
	v_max3_f32 v248, v248, v88, v89
	v_max3_f32 v248, v248, v90, v91
	ds_read_b64_tr_b16 v[200:201], v175 offset:0x1200
	ds_read_b64_tr_b16 v[202:203], v175 offset:0x1a00
	v_mfma_f32_32x32x16_bf16 v[0:15], v[146:149], v[204:207], v[0:15]
	v_max3_f32 v248, v248, v92, v93
	v_max3_f32 v248, v248, v94, v95
	v_max3_f32 v248, v248, v64, v65
	v_max3_f32 v248, v248, v66, v67
	ds_read_b64_tr_b16 v[204:205], v175 offset:0x2200
	ds_read_b64_tr_b16 v[206:207], v175 offset:0x2a00
	v_mfma_f32_32x32x16_bf16 v[0:15], v[192:195], v[208:211], v[0:15]
	v_max3_f32 v248, v248, v68, v69
	v_max3_f32 v248, v248, v70, v71
	v_max3_f32 v248, v248, v72, v73
	v_max3_f32 v248, v248, v74, v75
	ds_read_b64_tr_b16 v[208:209], v175 offset:0x3200
	ds_read_b64_tr_b16 v[210:211], v175 offset:0x3a00
	s_waitcnt lgkmcnt(0)
	v_mfma_f32_32x32x16_bf16 v[48:63], v[136:139], v[196:199], v[48:63]
	v_max3_f32 v248, v248, v76, v77
	v_max3_f32 v248, v248, v78, v79
	v_mov_b32_e32 v249, v248
	s_nop 1
	ds_read_b64_tr_b16 v[196:197], v175 offset:0x400
	ds_read_b64_tr_b16 v[198:199], v175 offset:0xc00
	v_mfma_f32_32x32x16_bf16 v[48:63], v[142:145], v[200:203], v[48:63]
	v_permlane32_swap_b32_e32 v248, v249
	v_max_f32_e32 v249, v249, v249
	v_max_f32_e32 v248, v248, v248
	v_max_f32_e32 v248, v248, v249
	ds_read_b64_tr_b16 v[200:201], v175 offset:0x1400
	ds_read_b64_tr_b16 v[202:203], v175 offset:0x1c00
	v_mfma_f32_32x32x16_bf16 v[48:63], v[146:149], v[204:207], v[48:63]
	v_sub_f32_e32 v249, v248, v140
	v_cmp_ge_f32_e32 vcc, s38, v249
	v_max_f32_e32 v249, v140, v140
	v_max_f32_e32 v248, v249, v248
	ds_read_b64_tr_b16 v[204:205], v175 offset:0x2400
	ds_read_b64_tr_b16 v[206:207], v175 offset:0x2c00
	v_mfma_f32_32x32x16_bf16 v[48:63], v[192:195], v[208:211], v[48:63]
	v_sub_f32_e32 v249, v140, v248
	v_mul_f32_e32 v249, 0x3e38aa3b, v249
	v_exp_f32_e32 v249, v249
	ds_read_b64_tr_b16 v[208:209], v175 offset:0x3400
	ds_read_b64_tr_b16 v[210:211], v175 offset:0x3c00
	s_waitcnt lgkmcnt(0)
	v_mfma_f32_32x32x16_bf16 v[32:47], v[136:139], v[196:199], v[32:47]
	s_cmp_eq_u64 vcc, exec
	s_cselect_b64 s[4:5], -1, 0
	v_cndmask_b32_e64 v251, v248, v140, s[4:5]
	ds_read_b64_tr_b16 v[196:197], v175 offset:0x600
	ds_read_b64_tr_b16 v[198:199], v175 offset:0xe00
	v_mfma_f32_32x32x16_bf16 v[32:47], v[142:145], v[200:203], v[32:47]
	v_mul_f32_e32 v250, 0xbe38aa3b, v251
	v_pk_fma_f32 v[80:81], v[80:81], s[44:45], v[250:251] op_sel_hi:[1,0,0]
	v_pk_fma_f32 v[82:83], v[82:83], s[44:45], v[250:251] op_sel_hi:[1,0,0]
	ds_read_b64_tr_b16 v[200:201], v175 offset:0x1600
	ds_read_b64_tr_b16 v[202:203], v175 offset:0x1e00
	v_mfma_f32_32x32x16_bf16 v[32:47], v[146:149], v[204:207], v[32:47]
	v_pk_fma_f32 v[84:85], v[84:85], s[44:45], v[250:251] op_sel_hi:[1,0,0]
	v_pk_fma_f32 v[86:87], v[86:87], s[44:45], v[250:251] op_sel_hi:[1,0,0]
	v_pk_fma_f32 v[88:89], v[88:89], s[44:45], v[250:251] op_sel_hi:[1,0,0]
	ds_read_b64_tr_b16 v[204:205], v175 offset:0x2600
	ds_read_b64_tr_b16 v[206:207], v175 offset:0x2e00
	v_mfma_f32_32x32x16_bf16 v[32:47], v[192:195], v[208:211], v[32:47]
	v_pk_fma_f32 v[90:91], v[90:91], s[44:45], v[250:251] op_sel_hi:[1,0,0]
	v_pk_fma_f32 v[92:93], v[92:93], s[44:45], v[250:251] op_sel_hi:[1,0,0]
	v_pk_fma_f32 v[94:95], v[94:95], s[44:45], v[250:251] op_sel_hi:[1,0,0]
	ds_read_b64_tr_b16 v[208:209], v175 offset:0x3600
	ds_read_b64_tr_b16 v[210:211], v175 offset:0x3e00
	s_waitcnt lgkmcnt(0)
	v_mfma_f32_32x32x16_bf16 v[16:31], v[136:139], v[196:199], v[16:31]
	v_mfma_f32_32x32x16_bf16 v[16:31], v[142:145], v[200:203], v[16:31]
	v_mfma_f32_32x32x16_bf16 v[16:31], v[146:149], v[204:207], v[16:31]
	v_mfma_f32_32x32x16_bf16 v[16:31], v[192:195], v[208:211], v[16:31]
	s_barrier
	s_waitcnt vmcnt(3)
	v_cndmask_b32_e64 v192, v249, 1.0, s[4:5]
	v_cmp_gt_f32_e32 vcc, 1.0, v192
	s_waitcnt vmcnt(3)
	ds_write_b128 v179, v[112:115]
	ds_write_b128 v180, v[116:119]
	ds_write_b128 v186, v[120:123] offset:32768
	s_cbranch_vccz .LBB0_1089
	s_and_saveexec_b64 s[8:9], s[6:7]
	ds_write_b32 v155, v192 offset:49280
	s_or_b64 exec, exec, s[8:9]
	s_waitcnt lgkmcnt(0)
	v_add_u32_e32 v137, v153, v178
	ds_read_b128 v[142:145], v137 offset:49376
	ds_read_b128 v[146:149], v137 offset:49344
	ds_read_b128 v[194:197], v137 offset:49312
	ds_read_b128 v[198:201], v137 offset:49280
	s_waitcnt lgkmcnt(3)
	v_pk_mul_f32 v[12:13], v[12:13], v[142:143]
	s_waitcnt lgkmcnt(2)
	v_pk_mul_f32 v[8:9], v[8:9], v[146:147]
	s_waitcnt lgkmcnt(1)
	v_pk_mul_f32 v[4:5], v[4:5], v[194:195]
	v_pk_mul_f32 v[14:15], v[14:15], v[144:145]
	v_pk_mul_f32 v[10:11], v[10:11], v[148:149]
	v_pk_mul_f32 v[6:7], v[6:7], v[196:197]
	s_waitcnt lgkmcnt(0)
	v_pk_mul_f32 v[2:3], v[2:3], v[200:201]
	v_pk_mul_f32 v[0:1], v[0:1], v[198:199]
	v_pk_mul_f32 v[60:61], v[60:61], v[142:143]
	v_pk_mul_f32 v[56:57], v[56:57], v[146:147]
	v_pk_mul_f32 v[52:53], v[52:53], v[194:195]
	v_pk_mul_f32 v[62:63], v[62:63], v[144:145]
	v_pk_mul_f32 v[58:59], v[58:59], v[148:149]
	v_pk_mul_f32 v[54:55], v[54:55], v[196:197]
	v_pk_mul_f32 v[50:51], v[50:51], v[200:201]
	v_pk_mul_f32 v[48:49], v[48:49], v[198:199]
	v_pk_mul_f32 v[44:45], v[44:45], v[142:143]
	v_pk_mul_f32 v[40:41], v[40:41], v[146:147]
	v_pk_mul_f32 v[36:37], v[36:37], v[194:195]
	v_pk_mul_f32 v[46:47], v[46:47], v[144:145]
	v_pk_mul_f32 v[42:43], v[42:43], v[148:149]
	v_pk_mul_f32 v[38:39], v[38:39], v[196:197]
	v_pk_mul_f32 v[34:35], v[34:35], v[200:201]
	v_pk_mul_f32 v[32:33], v[32:33], v[198:199]
	v_pk_mul_f32 v[28:29], v[28:29], v[142:143]
	v_pk_mul_f32 v[24:25], v[24:25], v[146:147]
	v_pk_mul_f32 v[20:21], v[20:21], v[194:195]
	v_pk_mul_f32 v[30:31], v[30:31], v[144:145]
	v_pk_mul_f32 v[26:27], v[26:27], v[148:149]
	v_pk_mul_f32 v[22:23], v[22:23], v[196:197]
	v_pk_mul_f32 v[18:19], v[18:19], v[200:201]
	v_pk_mul_f32 v[16:17], v[16:17], v[198:199]
.LBB0_1089:
	v_cndmask_b32_e64 v193, v248, v140, s[4:5]
	v_mul_f32_e32 v194, 0xbe38aa3b, v193
	v_exp_f32_e32 v136, v80
	v_exp_f32_e32 v137, v81
	v_exp_f32_e32 v138, v82
	v_exp_f32_e32 v139, v83
	v_exp_f32_e32 v147, v84
	v_exp_f32_e32 v149, v85
	v_exp_f32_e32 v150, v86
	v_exp_f32_e32 v151, v87
	v_exp_f32_e32 v140, v88
	v_exp_f32_e32 v141, v89
	v_exp_f32_e32 v142, v90
	v_exp_f32_e32 v143, v91
	v_exp_f32_e32 v144, v92
	v_exp_f32_e32 v145, v93
	v_exp_f32_e32 v146, v94
	v_exp_f32_e32 v148, v95
	v_fmamk_f32 v203, v64, 0x3e38aa3b, v194
	v_fmamk_f32 v204, v65, 0x3e38aa3b, v194
	v_fmamk_f32 v205, v66, 0x3e38aa3b, v194
	v_fmamk_f32 v206, v67, 0x3e38aa3b, v194
	v_fmamk_f32 v207, v68, 0x3e38aa3b, v194
	v_fmamk_f32 v196, v69, 0x3e38aa3b, v194
	v_fmamk_f32 v197, v70, 0x3e38aa3b, v194
	v_fmamk_f32 v198, v71, 0x3e38aa3b, v194
	v_fmamk_f32 v199, v72, 0x3e38aa3b, v194
	v_fmamk_f32 v200, v73, 0x3e38aa3b, v194
	v_fmamk_f32 v201, v74, 0x3e38aa3b, v194
	v_fmamk_f32 v202, v75, 0x3e38aa3b, v194
	v_fmamk_f32 v195, v76, 0x3e38aa3b, v194
	v_fmamk_f32 v208, v77, 0x3e38aa3b, v194
	v_fmamk_f32 v209, v78, 0x3e38aa3b, v194
	v_fmac_f32_e32 v194, 0x3e38aa3b, v79
	s_waitcnt lgkmcnt(0)
	s_barrier
	ds_read_b128 v[64:67], v181 offset:32768
	ds_read_b128 v[68:71], v181 offset:36864
	ds_read_b128 v[210:213], v187 offset:32768
	ds_read_b128 v[232:235], v187 offset:36864
	v_exp_f32_e32 v203, v203
	v_exp_f32_e32 v204, v204
	s_waitcnt lgkmcnt(3)
	v_mfma_f32_32x32x16_bf16 v[80:95], v[64:67], v[108:111], 0
	v_exp_f32_e32 v205, v205
	v_exp_f32_e32 v206, v206
	v_exp_f32_e32 v207, v207
	v_exp_f32_e32 v196, v196
	v_exp_f32_e32 v197, v197
	v_exp_f32_e32 v198, v198
	v_exp_f32_e32 v199, v199
	s_waitcnt lgkmcnt(2)
	v_mfma_f32_32x32x16_bf16 v[64:79], v[68:71], v[108:111], 0
	v_exp_f32_e32 v200, v200
	v_exp_f32_e32 v201, v201
	v_exp_f32_e32 v202, v202
	v_exp_f32_e32 v208, v208
	v_exp_f32_e32 v209, v209
	s_waitcnt lgkmcnt(1)
	v_mfma_f32_32x32x16_bf16 v[80:95], v[210:213], v[100:103], v[80:95]
	s_waitcnt lgkmcnt(0)
	v_mfma_f32_32x32x16_bf16 v[64:79], v[232:235], v[100:103], v[64:79]
	ds_read_b128 v[210:213], v188 offset:32768
	ds_read_b128 v[232:235], v188 offset:36864
	s_waitcnt lgkmcnt(1)
	v_mfma_f32_32x32x16_bf16 v[80:95], v[210:213], v[96:99], v[80:95]
	s_waitcnt lgkmcnt(0)
	v_mfma_f32_32x32x16_bf16 v[64:79], v[232:235], v[96:99], v[64:79]
	ds_read_b128 v[210:213], v176 offset:32768
	ds_read_b128 v[232:235], v176 offset:36864
	s_waitcnt lgkmcnt(1)
	v_mfma_f32_32x32x16_bf16 v[80:95], v[210:213], v[104:107], v[80:95]
	v_exp_f32_e32 v211, v194
	v_exp_f32_e32 v210, v195
	s_nop 0
	v_pk_add_f32 v[194:195], v[136:137], v[138:139]
	v_pk_add_f32 v[194:195], v[194:195], v[146:147]
	v_pk_add_f32 v[194:195], v[194:195], v[148:149]
	v_pk_add_f32 v[194:195], v[194:195], v[150:151]
	v_pk_add_f32 v[194:195], v[194:195], v[140:141]
	v_pk_add_f32 v[194:195], v[194:195], v[142:143]
	v_pk_add_f32 v[194:195], v[194:195], v[144:145]
	v_pk_add_f32 v[194:195], v[194:195], v[196:197]
	v_pk_add_f32 v[194:195], v[194:195], v[198:199]
	s_waitcnt lgkmcnt(0)
	v_mfma_f32_32x32x16_bf16 v[64:79], v[232:235], v[104:107], v[64:79]
	v_pk_add_f32 v[194:195], v[194:195], v[200:201]
	v_pk_add_f32 v[194:195], v[194:195], v[202:203]
	v_pk_add_f32 v[194:195], v[194:195], v[204:205]
	v_pk_add_f32 v[194:195], v[194:195], v[206:207]
	v_pk_add_f32 v[194:195], v[194:195], v[208:209]
	v_pk_add_f32 v[194:195], v[194:195], v[210:211]
	v_add_f32_e32 v194, v194, v195
	v_mov_b32_e32 v195, v194
	v_cvt_pk_bf16_f32 v136, v136, v137
	v_cvt_pk_bf16_f32 v137, v138, v139
	v_cvt_pk_bf16_f32 v138, v147, v149
	v_cvt_pk_bf16_f32 v139, v150, v151
	v_cvt_pk_bf16_f32 v140, v140, v141
	v_cvt_pk_bf16_f32 v141, v142, v143
	v_cvt_pk_bf16_f32 v142, v144, v145
	v_cvt_pk_bf16_f32 v143, v146, v148
	v_cvt_pk_bf16_f32 v144, v203, v204
	v_cvt_pk_bf16_f32 v145, v205, v206
	v_cvt_pk_bf16_f32 v146, v207, v196
	v_cvt_pk_bf16_f32 v147, v197, v198
	v_cvt_pk_bf16_f32 v148, v199, v200
	v_cvt_pk_bf16_f32 v149, v201, v202
	v_cvt_pk_bf16_f32 v150, v210, v208
	v_cvt_pk_bf16_f32 v151, v209, v211
	v_permlane32_swap_b32_e32 v194, v195
	v_permlane32_swap_b32_e32 v136, v138
	v_permlane32_swap_b32_e32 v137, v139
	v_permlane32_swap_b32_e32 v140, v142
	v_permlane32_swap_b32_e32 v141, v143
	v_permlane32_swap_b32_e32 v144, v146
	v_permlane32_swap_b32_e32 v145, v147
	v_permlane32_swap_b32_e32 v148, v150
	v_permlane32_swap_b32_e32 v149, v151
	s_cmp_ge_u32 s46, s47
	s_cselect_b64 s[8:9], -1, 0
	s_and_b64 vcc, exec, s[8:9]
	s_cbranch_vccnz .LBB0_1091
	v_add_co_u32_e32 v112, vcc, 0x18700000, v160
	s_nop 1
	v_addc_co_u32_e32 v113, vcc, 0, v161, vcc
	v_add_co_u32_e32 v116, vcc, 0x18740000, v160
	s_nop 1
	v_addc_co_u32_e32 v117, vcc, 0, v161, vcc
	v_add_co_u32_e32 v120, vcc, 0x18700000, v162
	global_load_dwordx4 v[112:115], v[112:113], off offset:3072
	s_nop 0
	global_load_dwordx4 v[116:119], v[116:117], off offset:3072
	v_addc_co_u32_e32 v121, vcc, 0, v163, vcc
	global_load_dwordx4 v[120:123], v[120:121], off offset:1536
.LBB0_1091:
	ds_read_b64_tr_b16 v[160:161], v174 offset:0
	ds_read_b64_tr_b16 v[162:163], v174 offset:0x800
	ds_read_b64_tr_b16 v[196:197], v174 offset:0x1000
	ds_read_b64_tr_b16 v[198:199], v174 offset:0x1800
	ds_read_b64_tr_b16 v[200:201], v174 offset:0x2000
	ds_read_b64_tr_b16 v[202:203], v174 offset:0x2800
	ds_read_b64_tr_b16 v[204:205], v174 offset:0x3000
	ds_read_b64_tr_b16 v[206:207], v174 offset:0x3800
	s_waitcnt lgkmcnt(0)
	s_nop 0
	v_mfma_f32_32x32x16_bf16 v[0:15], v[136:139], v[160:163], v[0:15]
	v_max_f32_e32 v248, v81, v81
	v_max_f32_e32 v249, v80, v80
	v_max_f32_e32 v248, v249, v248
	v_max3_f32 v248, v248, v82, v83
	ds_read_b64_tr_b16 v[160:161], v174 offset:0x200
	ds_read_b64_tr_b16 v[162:163], v174 offset:0xa00
	v_mfma_f32_32x32x16_bf16 v[0:15], v[140:143], v[196:199], v[0:15]
	v_max3_f32 v248, v248, v84, v85
	v_max3_f32 v248, v248, v86, v87
	v_max3_f32 v248, v248, v88, v89
	v_max3_f32 v248, v248, v90, v91
	ds_read_b64_tr_b16 v[196:197], v174 offset:0x1200
	ds_read_b64_tr_b16 v[198:199], v174 offset:0x1a00
	v_mfma_f32_32x32x16_bf16 v[0:15], v[144:147], v[200:203], v[0:15]
	v_max3_f32 v248, v248, v92, v93
	v_max3_f32 v248, v248, v94, v95
	v_max3_f32 v248, v248, v64, v65
	v_max3_f32 v248, v248, v66, v67
	ds_read_b64_tr_b16 v[200:201], v174 offset:0x2200
	ds_read_b64_tr_b16 v[202:203], v174 offset:0x2a00
	v_mfma_f32_32x32x16_bf16 v[0:15], v[148:151], v[204:207], v[0:15]
	v_max3_f32 v248, v248, v68, v69
	v_max3_f32 v248, v248, v70, v71
	v_max3_f32 v248, v248, v72, v73
	v_max3_f32 v248, v248, v74, v75
	ds_read_b64_tr_b16 v[204:205], v174 offset:0x3200
	ds_read_b64_tr_b16 v[206:207], v174 offset:0x3a00
	s_waitcnt lgkmcnt(0)
	v_mfma_f32_32x32x16_bf16 v[48:63], v[136:139], v[160:163], v[48:63]
	v_max3_f32 v248, v248, v76, v77
	v_max3_f32 v248, v248, v78, v79
	v_mov_b32_e32 v249, v248
	s_nop 1
	ds_read_b64_tr_b16 v[160:161], v174 offset:0x400
	ds_read_b64_tr_b16 v[162:163], v174 offset:0xc00
	v_mfma_f32_32x32x16_bf16 v[48:63], v[140:143], v[196:199], v[48:63]
	v_permlane32_swap_b32_e32 v248, v249
	v_max_f32_e32 v249, v249, v249
	v_max_f32_e32 v248, v248, v248
	v_max_f32_e32 v248, v248, v249
	ds_read_b64_tr_b16 v[196:197], v174 offset:0x1400
	ds_read_b64_tr_b16 v[198:199], v174 offset:0x1c00
	v_mfma_f32_32x32x16_bf16 v[48:63], v[144:147], v[200:203], v[48:63]
	v_sub_f32_e32 v249, v248, v193
	v_cmp_ge_f32_e32 vcc, s38, v249
	v_max_f32_e32 v249, v193, v193
	v_max_f32_e32 v248, v249, v248
	ds_read_b64_tr_b16 v[200:201], v174 offset:0x2400
	ds_read_b64_tr_b16 v[202:203], v174 offset:0x2c00
	v_mfma_f32_32x32x16_bf16 v[48:63], v[148:151], v[204:207], v[48:63]
	v_sub_f32_e32 v249, v193, v248
	v_mul_f32_e32 v249, 0x3e38aa3b, v249
	v_exp_f32_e32 v249, v249
	ds_read_b64_tr_b16 v[204:205], v174 offset:0x3400
	ds_read_b64_tr_b16 v[206:207], v174 offset:0x3c00
	s_waitcnt lgkmcnt(0)
	v_mfma_f32_32x32x16_bf16 v[32:47], v[136:139], v[160:163], v[32:47]
	s_cmp_eq_u64 vcc, exec
	s_cselect_b64 s[4:5], -1, 0
	v_cndmask_b32_e64 v251, v248, v193, s[4:5]
	ds_read_b64_tr_b16 v[160:161], v174 offset:0x600
	ds_read_b64_tr_b16 v[162:163], v174 offset:0xe00
	v_mfma_f32_32x32x16_bf16 v[32:47], v[140:143], v[196:199], v[32:47]
	v_mul_f32_e32 v250, 0xbe38aa3b, v251
	v_pk_fma_f32 v[80:81], v[80:81], s[44:45], v[250:251] op_sel_hi:[1,0,0]
	v_pk_fma_f32 v[82:83], v[82:83], s[44:45], v[250:251] op_sel_hi:[1,0,0]
	ds_read_b64_tr_b16 v[196:197], v174 offset:0x1600
	ds_read_b64_tr_b16 v[198:199], v174 offset:0x1e00
	v_mfma_f32_32x32x16_bf16 v[32:47], v[144:147], v[200:203], v[32:47]
	v_pk_fma_f32 v[84:85], v[84:85], s[44:45], v[250:251] op_sel_hi:[1,0,0]
	v_pk_fma_f32 v[86:87], v[86:87], s[44:45], v[250:251] op_sel_hi:[1,0,0]
	v_pk_fma_f32 v[88:89], v[88:89], s[44:45], v[250:251] op_sel_hi:[1,0,0]
	ds_read_b64_tr_b16 v[200:201], v174 offset:0x2600
	ds_read_b64_tr_b16 v[202:203], v174 offset:0x2e00
	v_mfma_f32_32x32x16_bf16 v[32:47], v[148:151], v[204:207], v[32:47]
	v_pk_fma_f32 v[90:91], v[90:91], s[44:45], v[250:251] op_sel_hi:[1,0,0]
	v_pk_fma_f32 v[92:93], v[92:93], s[44:45], v[250:251] op_sel_hi:[1,0,0]
	v_pk_fma_f32 v[94:95], v[94:95], s[44:45], v[250:251] op_sel_hi:[1,0,0]
	ds_read_b64_tr_b16 v[204:205], v174 offset:0x3600
	ds_read_b64_tr_b16 v[206:207], v174 offset:0x3e00
	s_waitcnt lgkmcnt(0)
	v_mfma_f32_32x32x16_bf16 v[16:31], v[136:139], v[160:163], v[16:31]
	v_mfma_f32_32x32x16_bf16 v[16:31], v[140:143], v[196:199], v[16:31]
	v_mfma_f32_32x32x16_bf16 v[16:31], v[144:147], v[200:203], v[16:31]
	v_mfma_f32_32x32x16_bf16 v[16:31], v[148:151], v[204:207], v[16:31]
	s_barrier
	s_waitcnt vmcnt(3)
	v_cndmask_b32_e64 v141, v249, 1.0, s[4:5]
	v_cmp_gt_f32_e32 vcc, 1.0, v141
	s_cmp_lg_u64 s[8:9], 0
	s_cbranch_scc0 .Lsw_da
	s_waitcnt vmcnt(0)

.LBB0_1095:
	v_cndmask_b32_e64 v140, v248, v193, s[4:5]
	v_mul_f32_e32 v124, 0xbe38aa3b, v140
	v_exp_f32_e32 v144, v80
	v_exp_f32_e32 v146, v81
	v_exp_f32_e32 v148, v82
	v_exp_f32_e32 v150, v83
	v_exp_f32_e32 v160, v84
	v_exp_f32_e32 v162, v85
	v_exp_f32_e32 v163, v86
	v_exp_f32_e32 v196, v87
	v_exp_f32_e32 v142, v88
	v_exp_f32_e32 v143, v89
	v_exp_f32_e32 v145, v90
	v_exp_f32_e32 v147, v91
	v_exp_f32_e32 v149, v92
	v_exp_f32_e32 v151, v93
	v_exp_f32_e32 v161, v94
	v_exp_f32_e32 v193, v95
	v_pk_fma_f32 v[138:139], v[64:65], s[44:45], v[124:125] op_sel_hi:[1,0,0]
	v_add_f32_e32 v64, v190, v191
	v_fmac_f32_e32 v64, v189, v173
	v_add_f32_e32 v173, v194, v195
	v_pk_fma_f32 v[136:137], v[66:67], s[44:45], v[124:125] op_sel_hi:[1,0,0]
	v_pk_fma_f32 v[132:133], v[68:69], s[44:45], v[124:125] op_sel_hi:[1,0,0]
	v_pk_fma_f32 v[128:129], v[70:71], s[44:45], v[124:125] op_sel_hi:[1,0,0]
	v_pk_fma_f32 v[126:127], v[72:73], s[44:45], v[124:125] op_sel_hi:[1,0,0]
	v_pk_fma_f32 v[134:135], v[74:75], s[44:45], v[124:125] op_sel_hi:[1,0,0]
	v_pk_fma_f32 v[130:131], v[76:77], s[44:45], v[124:125] op_sel_hi:[1,0,0]
	v_pk_fma_f32 v[124:125], v[78:79], s[44:45], v[124:125] op_sel_hi:[1,0,0]
	v_fmac_f32_e32 v173, v64, v192
	v_lshl_add_u64 v[156:157], v[156:157], 0, s[0:1]
	v_lshl_add_u64 v[158:159], v[158:159], 0, s[0:1]
	s_add_i32 s46, s46, 2
	s_and_b64 vcc, exec, s[8:9]
	s_waitcnt lgkmcnt(0)
	s_barrier
	s_cbranch_vccnz .LBB0_1097
	v_mov_b32_e32 v189, v141
	s_branch .LBB0_1085
